# v23 + XCD-local seams: last arriver of an XCD skips buffer_wbl2 and placement re-check (flag cached in a spill lane), issues L1 invalidate and XCD release together
# speedup vs baseline: 1.0055x; 1.0055x over previous
.Lmy_prio_done:
	v_writelane_b32 v246, s2, 0
	s_mov_b32 s101, 0
	s_nop 3
	v_writelane_b32 v246, s101, 60
	s_and_saveexec_b64 s[2:3], vcc
	v_lshl_add_u32 v1, v171, 2, 0
	v_add_u32_e32 v1, 0x20000, v1
	v_mov_b32_e32 v2, 0
	ds_write_b32 v1, v2
	s_or_b64 exec, exec, s[2:3]
	s_add_u32 s2, s76, 0x280000
	s_addc_u32 s3, s77, 0
	v_writelane_b32 v246, s2, 1
	s_sub_i32 s10, s79, s78
	s_cmp_lt_i32 s10, 2
	v_writelane_b32 v246, s3, 2
	s_mov_b32 s2, 0
	v_cmp_eq_u32_e32 vcc, 0, v171
	s_waitcnt lgkmcnt(0)
	s_barrier
	v_writelane_b32 v246, s2, 3
	s_cbranch_scc1 .LBB0_7
	s_getreg_b32 s2, hwreg(HW_REG_XCC_ID, 0, 4)
	s_and_b32 s2, s2, 15
	v_writelane_b32 v246, s2, 3
	s_and_saveexec_b64 s[2:3], vcc
	s_cbranch_execz .LBB0_6
	s_mov_b64 s[6:7], exec
	v_mbcnt_lo_u32_b32 v1, s6, 0
	v_mbcnt_hi_u32_b32 v1, s7, v1
	v_cmp_eq_u32_e32 vcc, 0, v1
	s_and_b64 s[8:9], exec, vcc
	s_mov_b64 exec, s[8:9]
	s_cbranch_execz .LBB0_6
	v_readlane_b32 s8, v246, 3
	s_bcnt1_i32_b64 s6, s[6:7]
	s_lshl_b32 s8, s8, 8
	v_mov_b32_e32 v2, s6
	v_readlane_b32 s6, v246, 1
	v_mov_b32_e32 v1, s8
	v_readlane_b32 s7, v246, 2
	s_nop 4
	global_atomic_add v1, v2, s[6:7] offset:1024
	v_readlane_b32 s8, v246, 3
	s_and_b32 s9, s74, 7
	s_lshl_b32 s9, s9, 2
	s_addk_i32 s9, 0x3700
	v_mov_b32_e32 v1, s9
	s_add_i32 s9, s8, 1
	v_mov_b32_e32 v2, s9
	s_sub_i32 s8, 16, s8
	v_mov_b32_e32 v3, s8
	global_atomic_umax v1, v2, s[6:7]
	global_atomic_umax v1, v3, s[6:7] offset:256

.LBB0_328:
	s_cmp_gt_i32 s79, 3
	s_cselect_b64 s[0:1], -1, 0
	s_and_b64 s[2:3], s[40:41], s[0:1]
	s_andn2_b64 vcc, exec, s[2:3]
	s_cbranch_vccnz .LBB0_378
	s_and_b64 vcc, exec, s[92:93]
	s_cbranch_vccz .Lg2_orig
	v_readlane_b32 s4, v246, 1
	v_readlane_b32 s5, v246, 2
	v_mov_b32_e32 v216, 0x3700
	s_nop 4
	global_load_dwordx4 v[200:203], v216, s[4:5] sc1
	global_load_dwordx4 v[204:207], v216, s[4:5] offset:16 sc1
	global_load_dwordx4 v[208:211], v216, s[4:5] offset:256 sc1
	global_load_dwordx4 v[212:215], v216, s[4:5] offset:272 sc1
	s_waitcnt vmcnt(0)
	v_add_u32_e32 v200, v200, v208
	v_xor_b32_e32 v200, 17, v200
	v_add_u32_e32 v201, v201, v209
	v_xor_b32_e32 v201, 17, v201
	v_add_u32_e32 v202, v202, v210
	v_xor_b32_e32 v202, 17, v202
	v_add_u32_e32 v203, v203, v211
	v_xor_b32_e32 v203, 17, v203
	v_add_u32_e32 v204, v204, v212
	v_xor_b32_e32 v204, 17, v204
	v_add_u32_e32 v205, v205, v213
	v_xor_b32_e32 v205, 17, v205
	v_add_u32_e32 v206, v206, v214
	v_xor_b32_e32 v206, 17, v206
	v_add_u32_e32 v207, v207, v215
	v_xor_b32_e32 v207, 17, v207
	v_or3_b32 v200, v200, v201, v202
	v_or3_b32 v203, v203, v204, v205
	v_or3_b32 v200, v200, v206, v207
	v_or_b32_e32 v200, v200, v203
	v_cmp_eq_u32_e32 vcc, 0, v200
	s_nop 1
	s_and_b64 vcc, vcc, exec
	s_cbranch_vccz .Lg2_orig
	s_mov_b32 s101, 1
	s_nop 3
	v_writelane_b32 v246, s101, 60
	s_barrier
	v_cmp_eq_u32_e32 vcc, 0, v171
	s_and_saveexec_b64 s[10:11], vcc
	s_cbranch_execz .Lg2_join
	s_and_b32 s6, s74, 7
	s_lshl_b32 s6, s6, 5
	s_lshr_b32 s7, s74, 3
	s_add_i32 s6, s6, s7
	s_and_b32 s7, s6, 3
	s_lshr_b32 s6, s6, 2
	s_lshl_b32 s6, s6, 6
	s_add_i32 s6, s6, 0xc080
	v_mov_b32_e32 v216, s6
	s_lshl_b32 s8, 1, s7
	v_mov_b32_e32 v217, s8
	s_cmp_eq_u32 s7, 3
	s_cbranch_scc1 .Lg2_np
	global_atomic_or v216, v217, s[4:5]

.LBB0_359:
	s_andn2_saveexec_b64 s[6:7], s[6:7]
	s_cbranch_execz .LBB0_377
	s_mov_b64 s[6:7], exec
	v_readlane_b32 s98, v246, 60
	s_cmp_eq_u32 s98, 1
	s_cbranch_scc0 .Llnw_slow0
	buffer_inv sc1
	v_mov_b32_e32 v0, 0x2000
	v_mov_b32_e32 v1, 1
	global_atomic_add v0, v1, s[4:5] offset:1024
	s_waitcnt vmcnt(0)
	s_branch .LBB0_377
.Llnw_slow0:
	buffer_wbl2 sc1
	v_readlane_b32 s98, v246, 1
	v_readlane_b32 s99, v246, 2
	v_mov_b32_e32 v20, 0x3700
	s_nop 4
	global_load_dwordx4 v[24:27], v20, s[98:99] sc1
	global_load_dwordx4 v[28:31], v20, s[98:99] offset:16 sc1
	global_load_dwordx4 v[32:35], v20, s[98:99] offset:256 sc1
	global_load_dwordx4 v[40:43], v20, s[98:99] offset:272 sc1
	buffer_inv sc1
	s_waitcnt lgkmcnt(0)
	s_waitcnt vmcnt(0)
	v_add_u32_e32 v24, v24, v32
	v_xor_b32_e32 v24, 17, v24
	v_add_u32_e32 v25, v25, v33
	v_xor_b32_e32 v25, 17, v25
	v_add_u32_e32 v26, v26, v34
	v_xor_b32_e32 v26, 17, v26
	v_add_u32_e32 v27, v27, v35
	v_xor_b32_e32 v27, 17, v27
	v_add_u32_e32 v28, v28, v40
	v_xor_b32_e32 v28, 17, v28
	v_add_u32_e32 v29, v29, v41
	v_xor_b32_e32 v29, 17, v29
	v_add_u32_e32 v30, v30, v42
	v_xor_b32_e32 v30, 17, v30
	v_add_u32_e32 v31, v31, v43
	v_xor_b32_e32 v31, 17, v31
	v_or3_b32 v24, v24, v25, v26
	v_or3_b32 v27, v27, v28, v29
	v_or3_b32 v24, v24, v30, v31
	v_or_b32_e32 v24, v24, v27
	v_cmp_eq_u32_e32 vcc, 0, v24
	s_and_b64 vcc, vcc, s[92:93]
	s_cbranch_vccnz .LBB0_376
	v_mbcnt_lo_u32_b32 v1, s6, 0
	v_mbcnt_hi_u32_b32 v1, s7, v1
	v_cmp_eq_u32_e32 vcc, 0, v1
	s_and_saveexec_b64 s[8:9], vcc
	s_cbranch_execz .LBB0_362
	s_bcnt1_i32_b64 s6, s[6:7]
	v_mov_b32_e32 v2, 0x283000
	v_mov_b32_e32 v3, s6
	global_atomic_add v2, v2, v3, s[76:77] offset:1024 sc0

.LBB0_859:
	s_andn2_saveexec_b64 s[8:9], s[8:9]
	s_cbranch_execz .LBB0_877
	s_mov_b64 s[8:9], exec
	v_readlane_b32 s98, v246, 60
	s_cmp_eq_u32 s98, 1
	s_cbranch_scc0 .Llnw_slow2
	buffer_inv sc1
	v_mov_b32_e32 v0, 0x2000
	v_mov_b32_e32 v1, 1
	global_atomic_add v0, v1, s[4:5] offset:1024
	s_waitcnt vmcnt(0)
	s_branch .LBB0_877
.Llnw_slow2:
	buffer_wbl2 sc1
	v_readlane_b32 s98, v246, 1
	v_readlane_b32 s99, v246, 2
	v_mov_b32_e32 v20, 0x3700
	s_nop 4
	global_load_dwordx4 v[24:27], v20, s[98:99] sc1
	global_load_dwordx4 v[28:31], v20, s[98:99] offset:16 sc1
	global_load_dwordx4 v[32:35], v20, s[98:99] offset:256 sc1
	global_load_dwordx4 v[40:43], v20, s[98:99] offset:272 sc1
	buffer_inv sc1
	s_waitcnt lgkmcnt(0)
	s_waitcnt vmcnt(0)
	v_add_u32_e32 v24, v24, v32
	v_xor_b32_e32 v24, 17, v24
	v_add_u32_e32 v25, v25, v33
	v_xor_b32_e32 v25, 17, v25
	v_add_u32_e32 v26, v26, v34
	v_xor_b32_e32 v26, 17, v26
	v_add_u32_e32 v27, v27, v35
	v_xor_b32_e32 v27, 17, v27
	v_add_u32_e32 v28, v28, v40
	v_xor_b32_e32 v28, 17, v28
	v_add_u32_e32 v29, v29, v41
	v_xor_b32_e32 v29, 17, v29
	v_add_u32_e32 v30, v30, v42
	v_xor_b32_e32 v30, 17, v30
	v_add_u32_e32 v31, v31, v43
	v_xor_b32_e32 v31, 17, v31
	v_or3_b32 v24, v24, v25, v26
	v_or3_b32 v27, v27, v28, v29
	v_or3_b32 v24, v24, v30, v31
	v_or_b32_e32 v24, v24, v27
	v_cmp_eq_u32_e32 vcc, 0, v24
	s_and_b64 vcc, vcc, s[92:93]
	s_cbranch_vccnz .LBB0_876
	v_mbcnt_lo_u32_b32 v1, s8, 0
	v_mbcnt_hi_u32_b32 v1, s9, v1
	v_cmp_eq_u32_e32 vcc, 0, v1
	s_and_saveexec_b64 s[10:11], vcc
	s_cbranch_execz .LBB0_862
	s_bcnt1_i32_b64 s8, s[8:9]
	v_mov_b32_e32 v2, 0x283000
	v_mov_b32_e32 v3, s8
	global_atomic_add v2, v2, v3, s[76:77] offset:1024 sc0
